# v82 + diff/fox stage loops: one vmcnt(0) before the LDS stores instead of a counted wait per store, '+0' SALU adds dropped
# baseline (speedup 1.0000x reference)
; #define LAS __attribute__((address_space(3)))
; #define DF_LOAD(T) do { const bf16* kg = Kb + (tokb + 128 * (T) + krow0) * 1024 + kgcol; const bf16* vg = Vb + (tokb + 128 * (T) + vkey0) * 1024 + vgcol; \
;         _Pragma("unroll") for (int c_ = 0; c_ < 4; ++c_) { kreg[c_] = *(const u32x4*)(kg + c_ * 8 * 1024); vreg[c_] = *(const u32x4*)(vg + c_ * 16 * 1024); } } while (0)
; #define DF_STORE(sb) do { LAS unsigned char* s_ = lds + (sb) * DST; \
;         _Pragma("unroll") for (int c_ = 0; c_ < 4; ++c_) { *(LAS u32x4*)(s_ + klds + c_ * 8 * 144) = kreg[c_]; *(LAS u32x4*)(s_ + vlds + c_ * 1024) = vreg[c_]; } } while (0)
; __device__ __forceinline__ void diff_phase(LAS unsigned char* lds, int L) {
;     ...
;         for (int it = 0; it < NT; ++it) {
;             const int T = NT - 1 - it;
;             if (it + 1 < NT) DF_LOAD(T - 1);
;             LAS const unsigned char* st = lds + (it & 1) * DST; LAS const unsigned char* kst = st + map * DKS;
;             if (2 * T + 1 <= th) tile_compute<MODE_DIFF, 4>(o, negm, m, thr, l, R, qr, nullptr, kst + 64 * 144, st + DVO + 16384, 128 * T + 64, qw0, r32, hi, lane, dtab);
;             if (2 * T <= th) tile_compute<MODE_DIFF, 4>(o, negm, m, thr, l, R, qr, nullptr, kst, st + DVO, 128 * T, qw0, r32, hi, lane, dtab);
;             if (it + 1 < NT) DF_STORE((it + 1) & 1);
.LBB0_188:
	s_bitcmp1_b32 s52, 0
	s_cselect_b32 s54, 0x11000, 0
	s_add_i32 s3, s54, s38
	s_cmp_ge_u32 s50, s48
	v_add3_u32 v222, s3, v210, v211
	s_cbranch_scc0 .LBB0_191
	s_cmp_gt_u32 s50, s48
	s_cbranch_scc0 .LBB0_198

.LBB0_205:
	s_bitcmp1_b32 s52, 0
	s_cselect_b32 s3, 0x11000, 0
	v_add_u32_e32 v0, s3, v207
	v_add_u32_e32 v1, s3, v204
	s_waitcnt vmcnt(0)
	ds_write_b128 v0, v[128:131]
	ds_write_b128 v1, v[132:135] offset:36864
	ds_write_b128 v0, v[140:143] offset:1152
	ds_write_b128 v1, v[156:159] offset:37888
	ds_write_b128 v0, v[160:163] offset:2304
	ds_write_b128 v1, v[164:167] offset:38912
	ds_write_b128 v0, v[168:171] offset:3456
	ds_write_b128 v1, v[172:175] offset:39936
	s_branch .LBB0_185

.LBB0_248:
	s_bitcmp1_b32 s43, 0
	s_cselect_b32 s3, 0x9000, 0
	v_add_u32_e32 v0, s3, v136
	s_waitcnt vmcnt(0)
	ds_write_b128 v0, v[116:119]
	ds_write_b128 v0, v[120:123] offset:9216
	v_add_u32_e32 v0, s3, v141
	ds_write_b128 v0, v[124:127] offset:18432
	ds_write_b128 v0, v[128:131] offset:19456
	s_and_saveexec_b64 s[22:23], s[4:5]
	s_cbranch_execz .LBB0_250
	v_mul_f32_e32 v0, 0xbfb8aa3b, v179
	v_bfe_u32 v1, v0, 16, 1
	v_add3_u32 v0, v0, v1, s89
	v_and_b32_e32 v1, 0xffff0000, v0
	v_fma_f32 v1, v179, s98, -v1
	v_bfe_u32 v3, v1, 16, 1
	v_add3_u32 v3, v1, v3, s89
	v_and_b32_e32 v3, 0xffff0000, v3
	v_sub_f32_e32 v1, v1, v3
	v_bfe_u32 v4, v1, 16, 1
	v_add3_u32 v1, v1, v4, s89
	v_lshrrev_b32_e32 v1, 16, v1
	v_or_b32_sdwa v0, v3, v0 dst_sel:DWORD dst_unused:UNUSED_PAD src0_sel:DWORD src1_sel:WORD_1
	v_mov_b32_e32 v3, v2
	v_add_u32_e32 v4, s3, v167
	ds_write_b128 v4, v[0:3] offset:34816
